# ffn adaLN-norm phase: L2 prefetch of the next iteration's two rows (one global_load_dword per lane, 128-B stride) behind the row loads; on top of the SrcC-fold attention
# speedup vs baseline: 1.0136x; 1.0136x over previous
; DI int get_tid() { int t = threadIdx.x; asm volatile("" : "+v"(t)); return t; }
; DI float* modp(const Params& p, int layer, int g, int chunk) { return (float*)(p.ws + OFF_MOD) + ((size_t)(layer * 9 + g) * 6 + chunk) * 1024; }
; DI void phase_norm(const Params& p, int layer, int which, bool from_input, bool skipctx) {
;   bf16_t* H = (bf16_t*)(p.ws + OFF_H);
;   const float* gam = (which ? p.g_ffn : p.g_mix) + layer * 1024;
;   const int tid_ = get_tid(); const int lane = tid_ & 63, w = tid_ >> 6;
;   float4 gg[4], s4[4], c4[4];
; #pragma unroll
;   for (int i = 0; i < 4; ++i) { gg[i] = *(const float4*)(gam + (i * 64 + lane) * 4); s4[i] = make_float4(0.f, 0.f, 0.f, 0.f); c4[i] = s4[i]; }
;   int gc = -1;
;   for (int t0 = (blockIdx.x * 8 + w) * 2; t0 < T; t0 += gridDim.x * 16) {
;     const int b = t0 / S, s = t0 - b * S, g = s < LC ? 8 : b;
;     if (skipctx && s < LC) continue;
;     if (g != gc) {
;       const float* sh = modp(p, layer, g, which ? 3 : 0);
;       const float* sc = modp(p, layer, g, which ? 4 : 1);
; #pragma unroll
;       for (int i = 0; i < 4; ++i) { s4[i] = *(const float4*)(sh + (i * 64 + lane) * 4); c4[i] = *(const float4*)(sc + (i * 64 + lane) * 4); }
;       gc = g;
;     }
;     float4 v[2][4]; float ss[2] = {0.f, 0.f};
; #pragma unroll
;     for (int u = 0; u < 2; ++u) {
;       const float* xr = from_input ? xrow_in(p, t0 + u) : xrow_ws(p, t0 + u);
; #pragma unroll
;       for (int i = 0; i < 4; ++i) { v[u][i] = *(const float4*)(xr + (i * 64 + lane) * 4); }
.LBB0_1789:
	s_or_b64 exec, exec, s[0:1]
	s_waitcnt lgkmcnt(0)
	v_mov_b32_e32 v0, v192
	s_barrier
	v_readlane_b32 s0, v250, 0
	v_ashrrev_i32_e32 v1, 5, v0
	v_and_b32_e32 v1, -2, v1
	v_add_u32_e32 v80, s0, v1
	s_mov_b32 s0, 0x8800
	v_cmp_gt_i32_e32 vcc, s0, v80
	s_and_saveexec_b64 s[36:37], vcc
	s_cbranch_execz .LBB0_1796
	v_readlane_b32 s64, v249, 46
	v_readlane_b32 s0, v254, 53
	v_readlane_b32 s65, v249, 47
	v_readlane_b32 s66, v249, 48
	v_readlane_b32 s67, v249, 49
	v_readlane_b32 s76, v249, 58
	v_readlane_b32 s77, v249, 59
	v_readlane_b32 s1, v254, 54
	v_readlane_b32 s78, v249, 60
	v_readlane_b32 s79, v249, 61
	s_mov_b64 s[64:65], s[76:77]
	s_lshl_b64 s[0:1], s[0:1], 2
	s_mov_b64 s[66:67], s[78:79]
	v_lshlrev_b32_e32 v0, 2, v0
	s_add_u32 s0, s66, s0
	v_and_b32_e32 v82, 0xfc, v0
	s_addc_u32 s1, s67, s1
	v_lshlrev_b32_e32 v12, 2, v82
	global_load_dwordx4 v[0:3], v12, s[0:1]
	global_load_dwordx4 v[4:7], v12, s[0:1] offset:1024
	global_load_dwordx4 v[8:11], v12, s[0:1] offset:2048
	s_nop 0
	global_load_dwordx4 v[12:15], v12, s[0:1] offset:3072
	v_readlane_b32 s0, v251, 55
	v_lshlrev_b32_e32 v220, 1, v82
	v_readlane_b32 s1, v251, 56
	v_or_b32_e32 v84, 0x100, v82
	v_or_b32_e32 v86, 0x200, v82
	v_lshl_add_u64 v[90:91], s[0:1], 0, v[220:221]
	v_mov_b32_e32 v220, v221
	v_or_b32_e32 v88, 0x300, v82
	v_mov_b32_e32 v83, -1
	s_mov_b64 s[40:41], 0
	v_mov_b64_e32 v[16:17], v[220:221]
	v_mov_b64_e32 v[18:19], v[220:221]
	v_mov_b64_e32 v[24:25], v[220:221]
	v_mov_b64_e32 v[26:27], v[220:221]
	v_mov_b64_e32 v[32:33], v[220:221]
	v_mov_b64_e32 v[34:35], v[220:221]
	v_mov_b64_e32 v[40:41], v[220:221]
	v_mov_b64_e32 v[42:43], v[220:221]
	v_mov_b64_e32 v[20:21], v[220:221]
	v_mov_b64_e32 v[22:23], v[220:221]
	v_mov_b64_e32 v[28:29], v[220:221]
	v_mov_b64_e32 v[30:31], v[220:221]
	v_mov_b64_e32 v[36:37], v[220:221]
	v_mov_b64_e32 v[38:39], v[220:221]
	v_mov_b64_e32 v[44:45], v[220:221]
	v_mov_b64_e32 v[46:47], v[220:221]
	v_readlane_b32 s68, v249, 50
	v_readlane_b32 s69, v249, 51
	v_readlane_b32 s70, v249, 52
	v_readlane_b32 s71, v249, 53
	v_readlane_b32 s72, v249, 54
	v_readlane_b32 s73, v249, 55
	v_readlane_b32 s74, v249, 56
	v_readlane_b32 s75, v249, 57
	v_and_b32_e32 v128, 63, v192
	v_lshlrev_b32_e32 v128, 7, v128
	v_mov_b32_e32 v129, 0
	s_branch .LBB0_1793
.LBB0_1791:
	s_or_b64 exec, exec, s[44:45]
	v_add_u32_e32 v92, 1, v80
	v_add_u32_e32 v54, 0xffffff00, v50
	v_mul_hi_i32 v58, v92, s51
	v_ashrrev_i32_e32 v49, 31, v48
	v_ashrrev_i32_e32 v51, 31, v50
	v_mov_b32_e32 v60, s93
	v_mov_b32_e32 v61, s83
	v_mov_b32_e32 v62, s92
	v_mov_b32_e32 v63, s29
	v_cndmask_b32_e32 v50, v54, v50, vcc
	v_cndmask_b32_e64 v54, 24, 20, vcc
	v_lshrrev_b32_e32 v59, 31, v58
	v_ashrrev_i32_e32 v58, 11, v58
	v_cndmask_b32_e32 v53, v60, v61, vcc
	v_cndmask_b32_e32 v52, v62, v63, vcc
	v_cndmask_b32_e32 v51, 0, v51, vcc
	v_lshlrev_b64 v[48:49], v54, v[48:49]
	v_add_u32_e32 v58, v58, v59
	v_lshl_add_u64 v[48:49], v[52:53], 0, v[48:49]
	v_lshlrev_b64 v[50:51], 12, v[50:51]
	v_mad_i32_i24 v64, v58, s80, v80
	v_lshl_add_u64 v[48:49], v[48:49], 0, v[50:51]
	v_add_u32_e32 v65, 1, v64
	v_lshl_add_u64 v[56:57], v[48:49], 0, v[220:221]
	v_cmp_gt_i32_e32 vcc, s50, v65
	global_load_dwordx4 v[48:51], v[56:57], off
	global_load_dwordx4 v[52:55], v[56:57], off offset:1024
	v_ashrrev_i32_e32 v59, 31, v58
	global_load_dwordx4 v[68:71], v[56:57], off offset:2048
	global_load_dwordx4 v[76:79], v[56:57], off offset:3072
	v_cndmask_b32_e64 v56, 24, 20, vcc
	v_ashrrev_i32_e32 v66, 31, v65
	v_add_u32_e32 v64, 0xffffff01, v64
	v_lshlrev_b64 v[56:57], v56, v[58:59]
	v_cndmask_b32_e32 v59, v60, v61, vcc
	v_cndmask_b32_e32 v58, v62, v63, vcc
	v_cndmask_b32_e32 v61, 0, v66, vcc
	v_cndmask_b32_e32 v60, v64, v65, vcc
	v_lshl_add_u64 v[56:57], v[58:59], 0, v[56:57]
	v_lshlrev_b64 v[58:59], 12, v[60:61]
	v_lshl_add_u64 v[56:57], v[56:57], 0, v[58:59]
	v_lshl_add_u64 v[56:57], v[56:57], 0, v[220:221]
	global_load_dwordx4 v[72:75], v[56:57], off
	global_load_dwordx4 v[64:67], v[56:57], off offset:1024
	global_load_dwordx4 v[60:63], v[56:57], off offset:2048
	s_nop 0
	global_load_dwordx4 v[56:59], v[56:57], off offset:3072
	v_add_u32_e32 v130, s91, v80
	v_cmp_gt_i32_e32 vcc, 0x8800, v130
	v_mul_hi_i32 v131, v80, s51
	s_nop 0
	v_cndmask_b32_e32 v130, v80, v130, vcc
	v_mul_hi_i32 v131, v130, s51
	v_lshrrev_b32_e32 v132, 31, v131
	v_ashrrev_i32_e32 v131, 11, v131
	v_add_u32_e32 v131, v131, v132
	v_mad_i32_i24 v132, v131, s80, v130
	v_cmp_gt_i32_e32 vcc, s50, v132
	v_add_u32_e32 v133, 0xffffff00, v132
	v_mov_b32_e32 v134, s92
	v_mov_b32_e32 v136, s29
	v_cndmask_b32_e32 v132, v133, v132, vcc
	v_cndmask_b32_e64 v133, 24, 20, vcc
	v_cndmask_b32_e32 v134, v134, v136, vcc
	v_mov_b32_e32 v135, s93
	v_mov_b32_e32 v136, s83
	v_mov_b32_e32 v137, 0
	v_cndmask_b32_e32 v135, v135, v136, vcc
	v_mov_b32_e32 v136, v131
	v_lshlrev_b64 v[136:137], v133, v[136:137]
	v_lshl_add_u64 v[134:135], v[134:135], 0, v[136:137]
	v_mov_b32_e32 v136, v132
	v_mov_b32_e32 v137, 0
	v_lshlrev_b64 v[136:137], 12, v[136:137]
	v_lshl_add_u64 v[134:135], v[134:135], 0, v[136:137]
	v_lshl_add_u64 v[134:135], v[134:135], 0, v[128:129]
	global_load_dword v138, v[134:135], off
	v_cmp_lt_i32_e32 vcc, v224, v207
	v_readlane_b32 s0, v251, 55
	v_readlane_b32 s1, v251, 56
	v_cndmask_b32_e32 v81, v205, v224, vcc
	v_lshlrev_b32_e32 v81, 2, v81
	v_cmp_lt_i32_e32 vcc, v225, v207
	s_waitcnt vmcnt(13)
	v_pk_add_f32 v[110:111], v[24:25], 1.0 op_sel_hi:[1,0]
	s_waitcnt vmcnt(11)
	v_pk_add_f32 v[116:117], v[34:35], 1.0 op_sel_hi:[1,0]
	v_cndmask_b32_e32 v85, v205, v225, vcc
	v_lshlrev_b32_e32 v85, 2, v85
	v_cmp_lt_i32_e32 vcc, v193, v207
	v_pk_add_f32 v[118:119], v[32:33], 1.0 op_sel_hi:[1,0]
	s_waitcnt vmcnt(9)
; DI void phase_norm(const Params& p, int layer, int which, bool from_input, bool skipctx) {
;     ...
; #pragma unroll
;     for (int u = 0; u < 2; ++u) {
; #pragma unroll
;       for (int i = 0; i < 4; ++i) ss[u] += v[u][i].x * v[u][i].x + v[u][i].y * v[u][i].y + v[u][i].z * v[u][i].z + v[u][i].w * v[u][i].w;
;       ss[u] = wave_sum(ss[u]);
;     }
	v_pk_add_f32 v[124:125], v[42:43], 1.0 op_sel_hi:[1,0]
	v_cndmask_b32_e32 v87, v205, v193, vcc
	v_lshlrev_b32_e32 v87, 2, v87
	v_cmp_lt_i32_e32 vcc, v197, v207
	v_lshlrev_b32_e32 v220, 1, v84
	s_waitcnt vmcnt(8)
	v_mov_b32_e32 v100, v49
	s_waitcnt vmcnt(7)
	v_mov_b32_e32 v101, v53
	s_waitcnt vmcnt(6)
	v_mov_b32_e32 v108, v69
	s_waitcnt vmcnt(5)
	v_mov_b32_e32 v109, v77
	v_mov_b32_e32 v98, v48
	v_mov_b32_e32 v99, v52
	v_mov_b32_e32 v106, v68
	v_mov_b32_e32 v107, v76
	v_pk_mul_f32 v[100:101], v[100:101], v[100:101]
	v_pk_mul_f32 v[108:109], v[108:109], v[108:109]
	v_mov_b32_e32 v94, v50
	v_mov_b32_e32 v95, v54
	v_mov_b32_e32 v102, v70
	v_mov_b32_e32 v103, v78
	v_pk_fma_f32 v[98:99], v[98:99], v[98:99], v[100:101]
	v_pk_fma_f32 v[100:101], v[106:107], v[106:107], v[108:109]
	s_waitcnt vmcnt(4)
	v_mov_b32_e32 v106, v73
	s_waitcnt vmcnt(3)
	v_mov_b32_e32 v107, v65
	v_mov_b32_e32 v96, v51
	v_mov_b32_e32 v97, v55
	v_pk_fma_f32 v[94:95], v[94:95], v[94:95], v[98:99]
	v_pk_fma_f32 v[98:99], v[102:103], v[102:103], v[100:101]
	v_mov_b32_e32 v102, v72
	v_mov_b32_e32 v103, v64
	v_pk_mul_f32 v[106:107], v[106:107], v[106:107]
	v_mov_b32_e32 v104, v71
	v_mov_b32_e32 v105, v79
	v_pk_fma_f32 v[94:95], v[96:97], v[96:97], v[94:95]
	v_mov_b32_e32 v96, v74
	v_mov_b32_e32 v97, v66
	v_pk_fma_f32 v[102:103], v[102:103], v[102:103], v[106:107]
	s_waitcnt vmcnt(2)
	v_mov_b32_e32 v106, v61
	s_waitcnt vmcnt(1)
	v_mov_b32_e32 v107, v57
	v_mov_b32_e32 v100, v75
	v_mov_b32_e32 v101, v67
	v_pk_fma_f32 v[96:97], v[96:97], v[96:97], v[102:103]
	v_pk_fma_f32 v[98:99], v[104:105], v[104:105], v[98:99]
	v_mov_b32_e32 v104, v60
	v_mov_b32_e32 v105, v56
	v_pk_mul_f32 v[106:107], v[106:107], v[106:107]
	v_pk_fma_f32 v[96:97], v[100:101], v[100:101], v[96:97]
	v_mov_b32_e32 v100, v62
	v_mov_b32_e32 v101, v58
	v_pk_fma_f32 v[104:105], v[104:105], v[104:105], v[106:107]
	v_mov_b32_e32 v102, v63
	v_mov_b32_e32 v103, v59
	v_pk_fma_f32 v[100:101], v[100:101], v[100:101], v[104:105]
	v_cndmask_b32_e32 v89, v205, v197, vcc
	v_pk_fma_f32 v[100:101], v[102:103], v[102:103], v[100:101]
	v_mov_b32_e32 v102, v96
	v_mov_b32_e32 v103, v94
	v_mov_b32_e32 v94, v97
	v_pk_add_f32 v[94:95], v[102:103], v[94:95]
	v_mov_b32_e32 v96, v100
	v_mov_b32_e32 v97, v98
	v_pk_add_f32 v[94:95], v[94:95], v[96:97]
	v_mov_b32_e32 v98, v101
	v_pk_add_f32 v[94:95], v[94:95], v[98:99]
	ds_bpermute_b32 v97, v81, v95
	ds_bpermute_b32 v96, v81, v94
	v_lshlrev_b32_e32 v89, 2, v89
	v_cmp_lt_i32_e32 vcc, v248, v207
	v_xor_b32_e32 v81, 1, v205
	v_pk_add_f32 v[98:99], v[18:19], 1.0 op_sel_hi:[1,0]
	s_waitcnt lgkmcnt(0)
	v_pk_add_f32 v[94:95], v[94:95], v[96:97]
	ds_bpermute_b32 v97, v85, v95
	ds_bpermute_b32 v96, v85, v94
	v_cndmask_b32_e32 v93, v205, v248, vcc
	v_lshlrev_b32_e32 v114, 2, v93
	v_cmp_lt_i32_e32 vcc, v81, v207
	v_ashrrev_i32_e32 v93, 31, v92
	s_waitcnt lgkmcnt(0)
	v_pk_add_f32 v[94:95], v[94:95], v[96:97]
	ds_bpermute_b32 v97, v87, v95
	ds_bpermute_b32 v96, v87, v94
	v_cndmask_b32_e32 v81, v205, v81, vcc
	v_lshlrev_b32_e32 v120, 2, v81
	v_ashrrev_i32_e32 v81, 31, v80
	v_lshlrev_b64 v[102:103], 11, v[80:81]
	s_waitcnt lgkmcnt(0)
	v_pk_add_f32 v[94:95], v[94:95], v[96:97]
	ds_bpermute_b32 v97, v89, v95
	ds_bpermute_b32 v96, v89, v94
	v_lshlrev_b64 v[92:93], 11, v[92:93]
	v_lshl_add_u64 v[104:105], v[90:91], 0, v[102:103]
	v_lshl_add_u64 v[106:107], v[90:91], 0, v[92:93]
	v_lshl_add_u64 v[102:103], s[0:1], 0, v[102:103]
	s_waitcnt lgkmcnt(0)
	v_pk_add_f32 v[94:95], v[94:95], v[96:97]
	ds_bpermute_b32 v97, v114, v95
	ds_bpermute_b32 v96, v114, v94
	v_lshl_add_u64 v[92:93], s[0:1], 0, v[92:93]
	s_mov_b32 s0, 0x3a800000
	v_pk_add_f32 v[100:101], v[16:17], 1.0 op_sel_hi:[1,0]
	v_pk_add_f32 v[108:109], v[26:27], 1.0 op_sel_hi:[1,0]
	s_waitcnt lgkmcnt(0)
	v_pk_add_f32 v[94:95], v[94:95], v[96:97]
	ds_bpermute_b32 v97, v120, v95
	ds_bpermute_b32 v96, v120, v94
	v_lshl_add_u64 v[112:113], v[102:103], 0, v[220:221]
	v_lshl_add_u64 v[114:115], v[92:93], 0, v[220:221]
	v_lshlrev_b32_e32 v220, 1, v86
	v_lshl_add_u64 v[120:121], v[102:103], 0, v[220:221]
	s_waitcnt lgkmcnt(0)
; DI unsigned pk2(float a, float b) { f2_t v = {a, b}; bf2_t r = __builtin_convertvector(v, bf2_t); return __builtin_bit_cast(unsigned, r); }
; DI void phase_norm(const Params& p, int layer, int which, bool from_input, bool skipctx) {
;     ...
; #pragma unroll
;     for (int i = 0; i < 4; ++i) {
;       const int k = (i * 64 + lane) * 4;
; #pragma unroll
;       for (int u = 0; u < 2; ++u) {
;         const float rstd = rsqrtf(ss[u] * (1.f / 1024.f) + EPS);
;         float o0 = v[u][i].x * rstd * gg[i].x * (1.f + c4[i].x) + s4[i].x, o1 = v[u][i].y * rstd * gg[i].y * (1.f + c4[i].y) + s4[i].y;
;         float o2 = v[u][i].z * rstd * gg[i].z * (1.f + c4[i].z) + s4[i].z, o3 = v[u][i].w * rstd * gg[i].w * (1.f + c4[i].w) + s4[i].w;
;         uint2 o; o.x = pk2(o0, o1); o.y = pk2(o2, o3);
;         *(uint2*)(H + (size_t)(t0 + u) * 1024 + k) = o;
;       }
;     }
	v_pk_add_f32 v[94:95], v[94:95], v[96:97]
	v_pk_add_f32 v[96:97], v[40:41], 1.0 op_sel_hi:[1,0]
	v_pk_fma_f32 v[94:95], v[94:95], s[0:1], v[196:197] op_sel_hi:[1,0,0]
	v_lshl_add_u64 v[122:123], v[92:93], 0, v[220:221]
	v_mul_f32_e32 v81, 0x4b800000, v95
	v_cmp_gt_f32_e32 vcc, s81, v95
	v_lshlrev_b32_e32 v220, 1, v88
	v_lshl_add_u64 v[102:103], v[102:103], 0, v[220:221]
	v_cndmask_b32_e32 v81, v95, v81, vcc
	v_rsq_f32_e32 v81, v81
	s_nop 0
	v_mul_f32_e32 v85, 0x45800000, v81
	v_cndmask_b32_e32 v126, v81, v85, vcc
	v_pk_mul_f32 v[48:49], v[48:49], v[126:127] op_sel_hi:[1,0]
	v_pk_mul_f32 v[50:51], v[50:51], v[126:127] op_sel_hi:[1,0]
	v_pk_mul_f32 v[48:49], v[0:1], v[48:49]
	v_pk_mul_f32 v[50:51], v[2:3], v[50:51]
	v_pk_fma_f32 v[48:49], v[100:101], v[48:49], v[20:21]
	v_pk_fma_f32 v[50:51], v[98:99], v[50:51], v[22:23]
	v_cvt_pk_bf16_f32 v48, v48, v49
	v_cvt_pk_bf16_f32 v49, v50, v51
	v_pk_mul_f32 v[50:51], v[52:53], v[126:127] op_sel_hi:[1,0]
	v_pk_mul_f32 v[52:53], v[54:55], v[126:127] op_sel_hi:[1,0]
	v_pk_mul_f32 v[50:51], v[4:5], v[50:51]
	v_pk_mul_f32 v[52:53], v[6:7], v[52:53]
	v_pk_fma_f32 v[50:51], v[110:111], v[50:51], v[28:29]
	v_pk_fma_f32 v[52:53], v[108:109], v[52:53], v[30:31]
	v_cvt_pk_bf16_f32 v50, v50, v51
	v_cvt_pk_bf16_f32 v51, v52, v53
	v_pk_mul_f32 v[52:53], v[68:69], v[126:127] op_sel_hi:[1,0]
	v_pk_mul_f32 v[54:55], v[70:71], v[126:127] op_sel_hi:[1,0]
	v_mul_f32_e32 v70, 0x4b800000, v94
	v_cmp_gt_f32_e32 vcc, s81, v94
	v_pk_mul_f32 v[52:53], v[8:9], v[52:53]
	v_pk_mul_f32 v[54:55], v[10:11], v[54:55]
	v_cndmask_b32_e32 v70, v94, v70, vcc
	v_pk_fma_f32 v[52:53], v[118:119], v[52:53], v[36:37]
	v_pk_fma_f32 v[54:55], v[116:117], v[54:55], v[38:39]
	v_rsq_f32_e32 v70, v70
	v_cvt_pk_bf16_f32 v52, v52, v53
	v_cvt_pk_bf16_f32 v53, v54, v55
	v_pk_mul_f32 v[54:55], v[76:77], v[126:127] op_sel_hi:[1,0]
	v_pk_mul_f32 v[68:69], v[78:79], v[126:127] op_sel_hi:[1,0]
	v_pk_mul_f32 v[54:55], v[12:13], v[54:55]
	v_pk_mul_f32 v[68:69], v[14:15], v[68:69]
	v_pk_fma_f32 v[54:55], v[96:97], v[54:55], v[44:45]
	v_pk_fma_f32 v[68:69], v[124:125], v[68:69], v[46:47]
	v_cvt_pk_bf16_f32 v54, v54, v55
	v_cvt_pk_bf16_f32 v55, v68, v69
	v_mul_f32_e32 v68, 0x45800000, v70
	v_cndmask_b32_e32 v68, v70, v68, vcc
	v_pk_mul_f32 v[70:71], v[72:73], v[68:69] op_sel_hi:[1,0]
	v_pk_mul_f32 v[72:73], v[74:75], v[68:69] op_sel_hi:[1,0]
	v_pk_mul_f32 v[64:65], v[64:65], v[68:69] op_sel_hi:[1,0]
	v_pk_mul_f32 v[66:67], v[66:67], v[68:69] op_sel_hi:[1,0]
	v_pk_mul_f32 v[60:61], v[60:61], v[68:69] op_sel_hi:[1,0]
	v_pk_mul_f32 v[62:63], v[62:63], v[68:69] op_sel_hi:[1,0]
	v_pk_mul_f32 v[70:71], v[0:1], v[70:71]
	v_pk_mul_f32 v[72:73], v[2:3], v[72:73]
	v_pk_mul_f32 v[64:65], v[4:5], v[64:65]
	v_pk_mul_f32 v[66:67], v[6:7], v[66:67]
	v_pk_mul_f32 v[60:61], v[8:9], v[60:61]
	v_pk_mul_f32 v[62:63], v[10:11], v[62:63]
	v_pk_fma_f32 v[70:71], v[100:101], v[70:71], v[20:21]
	v_pk_fma_f32 v[72:73], v[98:99], v[72:73], v[22:23]
	v_pk_fma_f32 v[64:65], v[110:111], v[64:65], v[28:29]
	v_pk_fma_f32 v[66:67], v[108:109], v[66:67], v[30:31]
	v_pk_fma_f32 v[60:61], v[118:119], v[60:61], v[36:37]
	v_pk_fma_f32 v[62:63], v[116:117], v[62:63], v[38:39]
	v_cvt_pk_bf16_f32 v70, v70, v71
	v_cvt_pk_bf16_f32 v71, v72, v73
	v_cvt_pk_bf16_f32 v64, v64, v65
	v_cvt_pk_bf16_f32 v65, v66, v67
	v_cvt_pk_bf16_f32 v60, v60, v61
	v_cvt_pk_bf16_f32 v61, v62, v63
	global_store_dwordx2 v[104:105], v[48:49], off
	global_store_dwordx2 v[106:107], v[70:71], off
	global_store_dwordx2 v[112:113], v[50:51], off
	global_store_dwordx2 v[114:115], v[64:65], off
	global_store_dwordx2 v[120:121], v[52:53], off
	global_store_dwordx2 v[122:123], v[60:61], off
	global_store_dwordx2 v[102:103], v[54:55], off
	v_pk_mul_f32 v[48:49], v[56:57], v[68:69] op_sel_hi:[1,0]
	v_pk_mul_f32 v[50:51], v[58:59], v[68:69] op_sel_hi:[1,0]
	v_pk_mul_f32 v[48:49], v[12:13], v[48:49]
	v_pk_mul_f32 v[50:51], v[14:15], v[50:51]
	v_pk_fma_f32 v[48:49], v[96:97], v[48:49], v[44:45]
	v_pk_fma_f32 v[50:51], v[124:125], v[50:51], v[46:47]
	v_cvt_pk_bf16_f32 v48, v48, v49
	v_cvt_pk_bf16_f32 v49, v50, v51
	v_lshl_add_u64 v[50:51], v[92:93], 0, v[220:221]
	global_store_dwordx2 v[50:51], v[48:49], off
